# P1 bf16 epilogue block: 8-byte store pairs merged into 16-byte stores via v_permlane16_swap (as already done in P4 and P6)
# speedup vs baseline: 1.0089x; 1.0089x over previous
; __device__ __forceinline__ unsigned cvt_pk_bf16(float lo, float hi) { unsigned r; asm volatile("v_cvt_pk_bf16_f32 %0, %1, %2" : "=v"(r) : "v"(lo), "v"(hi)); return r; }
;     __device__ __forceinline__ void operator()(const f32x4 (&acc)[2][2][4][2], const Unit& u, int wr, int wc, int fr, int fq) const {
;     ...
;                 for (int m = 0; m < 4; ++m) { bf16_t* rowp = hb + (size_t)(row0 + ai * HALF + m * 16) * ldc + col0;
; #pragma unroll
;                     for (int bj = 0; bj < 2; ++bj)
; #pragma unroll
;                         for (int n = 0; n < 2; ++n) { const f32x4 v = acc[ai][bj][m][n] * sc; u32x2 w; w.x = cvt_pk_bf16(v[0], v[1]); w.y = cvt_pk_bf16(v[2], v[3]);
;                             if (ldc == 4096) __builtin_nontemporal_store(w, (u32x2*)(rowp + bj * HALF + n * 16)); else *(u32x2*)(rowp + bj * HALF + n * 16) = w; } }
.LBB0_192:
	v_lshlrev_b32_e32 v132, 1, v134
	v_mad_u64_u32 v[172:173], s[0:1], s66, v169, 0
	v_lshl_add_u64 v[144:145], s[70:71], 0, v[132:133]
	v_mbcnt_lo_u32_b32 v252, -1, 0
	v_mbcnt_hi_u32_b32 v252, -1, v252
	v_and_b32_e32 v250, 16, v252
	v_lshrrev_b32_e32 v252, 1, v250
	v_add_u32_e32 v250, v250, v252
	v_mov_b32_e32 v251, 0
	v_lshl_add_u64 v[144:145], v[144:145], 0, v[250:251]
	v_add3_u32 v173, v173, v163, v170
	v_lshl_add_u64 v[170:171], v[172:173], 1, v[144:145]
	v_pk_mul_f32 v[124:125], v[124:125], s[8:9] op_sel_hi:[1,0]
	v_pk_mul_f32 v[120:121], v[120:121], s[8:9] op_sel_hi:[1,0]
	v_pk_mul_f32 v[116:117], v[116:117], s[8:9] op_sel_hi:[1,0]
	v_pk_mul_f32 v[108:109], v[108:109], s[8:9] op_sel_hi:[1,0]
	v_pk_mul_f32 v[126:127], v[126:127], s[8:9] op_sel_hi:[1,0]
	v_cvt_pk_bf16_f32 v234, v124, v125
	v_pk_mul_f32 v[122:123], v[122:123], s[8:9] op_sel_hi:[1,0]
	v_cvt_pk_bf16_f32 v235, v126, v127
	v_cvt_pk_bf16_f32 v236, v120, v121
	v_cvt_pk_bf16_f32 v237, v122, v123
	s_nop 1
	v_permlane16_swap_b32_e32 v234, v236
	v_permlane16_swap_b32_e32 v235, v237
	flat_store_dwordx4 v[170:171], v[234:237]
	v_pk_mul_f32 v[118:119], v[118:119], s[8:9] op_sel_hi:[1,0]
	v_cvt_pk_bf16_f32 v238, v116, v117
	v_pk_mul_f32 v[110:111], v[110:111], s[8:9] op_sel_hi:[1,0]
	v_cvt_pk_bf16_f32 v239, v118, v119
	v_cvt_pk_bf16_f32 v240, v108, v109
	v_cvt_pk_bf16_f32 v241, v110, v111
	s_nop 1
	v_permlane16_swap_b32_e32 v238, v240
	v_permlane16_swap_b32_e32 v239, v241
	flat_store_dwordx4 v[170:171], v[238:241] offset:256
	v_mad_u64_u32 v[108:109], s[0:1], s66, v167, 0
	v_add3_u32 v109, v109, v163, v168
	v_lshl_add_u64 v[108:109], v[108:109], 1, v[144:145]
	v_pk_mul_f32 v[112:113], v[112:113], s[8:9] op_sel_hi:[1,0]
	v_pk_mul_f32 v[104:105], v[104:105], s[8:9] op_sel_hi:[1,0]
	v_pk_mul_f32 v[100:101], v[100:101], s[8:9] op_sel_hi:[1,0]
	v_pk_mul_f32 v[92:93], v[92:93], s[8:9] op_sel_hi:[1,0]
	v_pk_mul_f32 v[110:111], v[114:115], s[8:9] op_sel_hi:[1,0]
	v_cvt_pk_bf16_f32 v242, v112, v113
	v_pk_mul_f32 v[106:107], v[106:107], s[8:9] op_sel_hi:[1,0]
	v_cvt_pk_bf16_f32 v243, v110, v111
	v_cvt_pk_bf16_f32 v244, v104, v105
	v_cvt_pk_bf16_f32 v245, v106, v107
	s_nop 1
	v_permlane16_swap_b32_e32 v242, v244
	v_permlane16_swap_b32_e32 v243, v245
	flat_store_dwordx4 v[108:109], v[242:245]
	v_pk_mul_f32 v[102:103], v[102:103], s[8:9] op_sel_hi:[1,0]
	v_cvt_pk_bf16_f32 v246, v100, v101
	v_pk_mul_f32 v[94:95], v[94:95], s[8:9] op_sel_hi:[1,0]
	v_cvt_pk_bf16_f32 v247, v102, v103
	v_cvt_pk_bf16_f32 v248, v92, v93
	v_cvt_pk_bf16_f32 v249, v94, v95
	s_nop 1
	v_permlane16_swap_b32_e32 v246, v248
	v_permlane16_swap_b32_e32 v247, v249
	flat_store_dwordx4 v[108:109], v[246:249] offset:256
	v_mad_u64_u32 v[92:93], s[0:1], s66, v165, 0
	v_add3_u32 v93, v93, v163, v166
	v_lshl_add_u64 v[92:93], v[92:93], 1, v[144:145]
	v_pk_mul_f32 v[96:97], v[96:97], s[8:9] op_sel_hi:[1,0]
	v_pk_mul_f32 v[88:89], v[88:89], s[8:9] op_sel_hi:[1,0]
	v_pk_mul_f32 v[84:85], v[84:85], s[8:9] op_sel_hi:[1,0]
	v_pk_mul_f32 v[76:77], v[76:77], s[8:9] op_sel_hi:[1,0]
	v_pk_mul_f32 v[94:95], v[98:99], s[8:9] op_sel_hi:[1,0]
	v_cvt_pk_bf16_f32 v234, v96, v97
	v_pk_mul_f32 v[90:91], v[90:91], s[8:9] op_sel_hi:[1,0]
	v_cvt_pk_bf16_f32 v235, v94, v95
	v_cvt_pk_bf16_f32 v236, v88, v89
	v_cvt_pk_bf16_f32 v237, v90, v91
	s_nop 1
	v_permlane16_swap_b32_e32 v234, v236
	v_permlane16_swap_b32_e32 v235, v237
	flat_store_dwordx4 v[92:93], v[234:237]
	v_pk_mul_f32 v[86:87], v[86:87], s[8:9] op_sel_hi:[1,0]
	v_cvt_pk_bf16_f32 v238, v84, v85
	v_pk_mul_f32 v[78:79], v[78:79], s[8:9] op_sel_hi:[1,0]
	v_cvt_pk_bf16_f32 v239, v86, v87
	v_cvt_pk_bf16_f32 v240, v76, v77
	v_cvt_pk_bf16_f32 v241, v78, v79
	s_nop 1
	v_permlane16_swap_b32_e32 v238, v240
	v_permlane16_swap_b32_e32 v239, v241
	flat_store_dwordx4 v[92:93], v[238:241] offset:256
	v_mad_u64_u32 v[76:77], s[0:1], s66, v162, 0
	v_add3_u32 v77, v77, v163, v164
	v_lshl_add_u64 v[76:77], v[76:77], 1, v[144:145]
	v_pk_mul_f32 v[80:81], v[80:81], s[8:9] op_sel_hi:[1,0]
	v_pk_mul_f32 v[72:73], v[72:73], s[8:9] op_sel_hi:[1,0]
	v_pk_mul_f32 v[68:69], v[68:69], s[8:9] op_sel_hi:[1,0]
	v_pk_mul_f32 v[64:65], v[64:65], s[8:9] op_sel_hi:[1,0]
	v_pk_mul_f32 v[78:79], v[82:83], s[8:9] op_sel_hi:[1,0]
	v_cvt_pk_bf16_f32 v242, v80, v81
	v_pk_mul_f32 v[74:75], v[74:75], s[8:9] op_sel_hi:[1,0]
	v_cvt_pk_bf16_f32 v243, v78, v79
	v_cvt_pk_bf16_f32 v244, v72, v73
	v_cvt_pk_bf16_f32 v245, v74, v75
	s_nop 1
	v_permlane16_swap_b32_e32 v242, v244
	v_permlane16_swap_b32_e32 v243, v245
	flat_store_dwordx4 v[76:77], v[242:245]
	v_pk_mul_f32 v[70:71], v[70:71], s[8:9] op_sel_hi:[1,0]
	v_cvt_pk_bf16_f32 v246, v68, v69
	v_pk_mul_f32 v[66:67], v[66:67], s[8:9] op_sel_hi:[1,0]
	v_cvt_pk_bf16_f32 v247, v70, v71
	v_cvt_pk_bf16_f32 v248, v64, v65
; __device__ __forceinline__ unsigned cvt_pk_bf16(float lo, float hi) { unsigned r; asm volatile("v_cvt_pk_bf16_f32 %0, %1, %2" : "=v"(r) : "v"(lo), "v"(hi)); return r; }
;     __device__ __forceinline__ void operator()(const f32x4 (&acc)[2][2][4][2], const Unit& u, int wr, int wc, int fr, int fq) const {
;     ...
;                 for (int m = 0; m < 4; ++m) { bf16_t* rowp = hb + (size_t)(row0 + ai * HALF + m * 16) * ldc + col0;
; #pragma unroll
;                     for (int bj = 0; bj < 2; ++bj)
; #pragma unroll
;                         for (int n = 0; n < 2; ++n) { const f32x4 v = acc[ai][bj][m][n] * sc; u32x2 w; w.x = cvt_pk_bf16(v[0], v[1]); w.y = cvt_pk_bf16(v[2], v[3]);
;                             if (ldc == 4096) __builtin_nontemporal_store(w, (u32x2*)(rowp + bj * HALF + n * 16)); else *(u32x2*)(rowp + bj * HALF + n * 16) = w; } }
	v_cvt_pk_bf16_f32 v249, v66, v67
	s_nop 1
	v_permlane16_swap_b32_e32 v246, v248
	v_permlane16_swap_b32_e32 v247, v249
	flat_store_dwordx4 v[76:77], v[246:249] offset:256
	v_mul_lo_u32 v66, s66, v161
	v_mad_u64_u32 v[64:65], s[0:1], s66, v159, 0
	v_add3_u32 v65, v65, v66, v160
	v_lshl_add_u64 v[64:65], v[64:65], 1, v[144:145]
	v_pk_mul_f32 v[60:61], v[60:61], s[8:9] op_sel_hi:[1,0]
	v_pk_mul_f32 v[56:57], v[56:57], s[8:9] op_sel_hi:[1,0]
	v_pk_mul_f32 v[52:53], v[52:53], s[8:9] op_sel_hi:[1,0]
	v_pk_mul_f32 v[44:45], v[44:45], s[8:9] op_sel_hi:[1,0]
	v_pk_mul_f32 v[62:63], v[62:63], s[8:9] op_sel_hi:[1,0]
	v_cvt_pk_bf16_f32 v234, v60, v61
	v_pk_mul_f32 v[58:59], v[58:59], s[8:9] op_sel_hi:[1,0]
	v_cvt_pk_bf16_f32 v235, v62, v63
	v_cvt_pk_bf16_f32 v236, v56, v57
	v_cvt_pk_bf16_f32 v237, v58, v59
	s_nop 1
	v_permlane16_swap_b32_e32 v234, v236
	v_permlane16_swap_b32_e32 v235, v237
	flat_store_dwordx4 v[64:65], v[234:237]
	v_pk_mul_f32 v[54:55], v[54:55], s[8:9] op_sel_hi:[1,0]
	v_cvt_pk_bf16_f32 v238, v52, v53
	v_pk_mul_f32 v[46:47], v[46:47], s[8:9] op_sel_hi:[1,0]
	v_cvt_pk_bf16_f32 v239, v54, v55
	v_cvt_pk_bf16_f32 v240, v44, v45
	v_cvt_pk_bf16_f32 v241, v46, v47
	s_nop 1
	v_permlane16_swap_b32_e32 v238, v240
	v_permlane16_swap_b32_e32 v239, v241
	flat_store_dwordx4 v[64:65], v[238:241] offset:256
	v_mul_lo_u32 v46, s66, v158
	v_mad_u64_u32 v[44:45], s[0:1], s66, v156, 0
	v_add3_u32 v45, v45, v46, v157
	v_lshl_add_u64 v[44:45], v[44:45], 1, v[144:145]
	v_pk_mul_f32 v[48:49], v[48:49], s[8:9] op_sel_hi:[1,0]
	v_pk_mul_f32 v[40:41], v[40:41], s[8:9] op_sel_hi:[1,0]
	v_pk_mul_f32 v[36:37], v[36:37], s[8:9] op_sel_hi:[1,0]
	v_pk_mul_f32 v[28:29], v[28:29], s[8:9] op_sel_hi:[1,0]
	v_pk_mul_f32 v[46:47], v[50:51], s[8:9] op_sel_hi:[1,0]
	v_cvt_pk_bf16_f32 v242, v48, v49
	v_pk_mul_f32 v[42:43], v[42:43], s[8:9] op_sel_hi:[1,0]
	v_cvt_pk_bf16_f32 v243, v46, v47
	v_cvt_pk_bf16_f32 v244, v40, v41
	v_cvt_pk_bf16_f32 v245, v42, v43
	s_nop 1
	v_permlane16_swap_b32_e32 v242, v244
	v_permlane16_swap_b32_e32 v243, v245
	flat_store_dwordx4 v[44:45], v[242:245]
	v_pk_mul_f32 v[38:39], v[38:39], s[8:9] op_sel_hi:[1,0]
	v_cvt_pk_bf16_f32 v246, v36, v37
	v_pk_mul_f32 v[30:31], v[30:31], s[8:9] op_sel_hi:[1,0]
	v_cvt_pk_bf16_f32 v247, v38, v39
	v_cvt_pk_bf16_f32 v248, v28, v29
	v_cvt_pk_bf16_f32 v249, v30, v31
	s_nop 1
	v_permlane16_swap_b32_e32 v246, v248
	v_permlane16_swap_b32_e32 v247, v249
	flat_store_dwordx4 v[44:45], v[246:249] offset:256
	v_mul_lo_u32 v30, s66, v155
	v_mad_u64_u32 v[28:29], s[0:1], s66, v153, 0
	v_add3_u32 v29, v29, v30, v154
	v_lshl_add_u64 v[28:29], v[28:29], 1, v[144:145]
	v_pk_mul_f32 v[32:33], v[32:33], s[8:9] op_sel_hi:[1,0]
	v_pk_mul_f32 v[24:25], v[24:25], s[8:9] op_sel_hi:[1,0]
	v_pk_mul_f32 v[20:21], v[20:21], s[8:9] op_sel_hi:[1,0]
	v_pk_mul_f32 v[12:13], v[12:13], s[8:9] op_sel_hi:[1,0]
	v_pk_mul_f32 v[30:31], v[34:35], s[8:9] op_sel_hi:[1,0]
	v_cvt_pk_bf16_f32 v234, v32, v33
	v_pk_mul_f32 v[26:27], v[26:27], s[8:9] op_sel_hi:[1,0]
	v_cvt_pk_bf16_f32 v235, v30, v31
	v_cvt_pk_bf16_f32 v236, v24, v25
	v_cvt_pk_bf16_f32 v237, v26, v27
	s_nop 1
	v_permlane16_swap_b32_e32 v234, v236
	v_permlane16_swap_b32_e32 v235, v237
	flat_store_dwordx4 v[28:29], v[234:237]
	v_pk_mul_f32 v[22:23], v[22:23], s[8:9] op_sel_hi:[1,0]
	v_cvt_pk_bf16_f32 v238, v20, v21
	v_pk_mul_f32 v[14:15], v[14:15], s[8:9] op_sel_hi:[1,0]
	v_cvt_pk_bf16_f32 v239, v22, v23
	v_cvt_pk_bf16_f32 v240, v12, v13
	v_cvt_pk_bf16_f32 v241, v14, v15
	s_nop 1
	v_permlane16_swap_b32_e32 v238, v240
	v_permlane16_swap_b32_e32 v239, v241
	flat_store_dwordx4 v[28:29], v[238:241] offset:256
	v_mul_lo_u32 v14, s66, v152
	v_mad_u64_u32 v[12:13], s[0:1], s66, v150, 0
	v_add3_u32 v13, v13, v14, v151
	v_lshl_add_u64 v[12:13], v[12:13], 1, v[144:145]
	v_pk_mul_f32 v[16:17], v[16:17], s[8:9] op_sel_hi:[1,0]
	v_pk_mul_f32 v[8:9], v[8:9], s[8:9] op_sel_hi:[1,0]
	v_pk_mul_f32 v[4:5], v[4:5], s[8:9] op_sel_hi:[1,0]
	v_pk_mul_f32 v[0:1], v[0:1], s[8:9] op_sel_hi:[1,0]
	v_pk_mul_f32 v[14:15], v[18:19], s[8:9] op_sel_hi:[1,0]
	v_cvt_pk_bf16_f32 v242, v16, v17
	v_pk_mul_f32 v[10:11], v[10:11], s[8:9] op_sel_hi:[1,0]
	v_cvt_pk_bf16_f32 v243, v14, v15
	v_cvt_pk_bf16_f32 v244, v8, v9
	v_cvt_pk_bf16_f32 v245, v10, v11
	s_nop 1
	v_permlane16_swap_b32_e32 v242, v244
	v_permlane16_swap_b32_e32 v243, v245
	flat_store_dwordx4 v[12:13], v[242:245]
	v_pk_mul_f32 v[6:7], v[6:7], s[8:9] op_sel_hi:[1,0]
	v_cvt_pk_bf16_f32 v246, v4, v5
	v_pk_mul_f32 v[2:3], v[2:3], s[8:9] op_sel_hi:[1,0]
	v_cvt_pk_bf16_f32 v247, v6, v7
	v_cvt_pk_bf16_f32 v248, v0, v1
	v_cvt_pk_bf16_f32 v249, v2, v3
	s_nop 1
	v_permlane16_swap_b32_e32 v246, v248
	v_permlane16_swap_b32_e32 v247, v249
	flat_store_dwordx4 v[12:13], v[246:249] offset:256
